# attention: per-wave early stop of tile bodies (same f32-resolution criterion per wave) on top of copy removal
# speedup vs baseline: 1.0208x; 1.0086x over previous
; #define LAS __attribute__((address_space(3)))
; __device__ __forceinline__ float lane0(float v) { return __builtin_bit_cast(float, __builtin_amdgcn_readfirstlane(__builtin_bit_cast(int, v))); }
; __device__ __forceinline__ void attn_unit(const UnitDesc& u, LAS unsigned char* shm, float qkmax, float thresh) {
;     ...
;     const float ci = -Rown * LOG2E - qkmax;
;     const float kbq0 = Rq0 * LOG2E;
;     const int qabs = u.q0 + wid * 32 + r32;
;     float l_reg = 0.f; f32x16 o[2]; o[0] = f32x16{}; o[1] = f32x16{};
;     float lA = lfb[1], lB = lfb[2], lC = lfb[3];
;     { const float lf = lfb[0]; const float inc = inc4[0]; wsf[lane] = (inc - lf) * LOG2E; carry = lane0(inc);
;       *(LAS u32x4*)kdst = kreg; *(LAS u32x4*)vdst = vreg;
;       asm volatile("" : "+v"(qr[0]), "+v"(qr[1]), "+v"(qr[2]), "+v"(qr[3]));
;       asm volatile("s_waitcnt vmcnt(0)" : "+v"(kA), "+v"(vA), "+v"(kB), "+v"(vB), "+v"(kC), "+v"(vC) :: "memory"); }
;     int slot = 0, tile = NT - 1; bool stop = false;
.LBB0_772:
	v_lshlrev_b32_e32 v15, 1, v12
	s_lshl_b32 s12, s52, 10
	v_and_b32_e32 v15, 32, v15
	s_add_i32 s13, 0, 0x2000
	v_lshlrev_b32_e32 v142, 2, v136
	v_lshrrev_b32_e32 v12, 2, v12
	s_add_i32 s12, s12, 0
	v_add_u32_e32 v15, s13, v15
	v_and_or_b32 v12, v12, 3, v142
	s_lshl_b32 s13, s52, 9
	v_lshlrev_b32_e32 v12, 6, v12
	s_sub_i32 s53, s12, s13
	v_add_u32_e32 v147, s66, v10
	v_sub_f32_e32 v10, v0, v14
	v_lshl_add_u32 v143, v137, 4, s12
	v_add3_u32 v144, v15, v13, v12
	s_mov_b32 s12, 0xbfb8aa3b
	s_waitcnt lgkmcnt(0)
	v_mul_f32_e32 v146, 0x3fb8aa3b, v11
	v_mul_f32_e32 v10, 0x3fb8aa3b, v10
	v_lshl_add_u32 v11, v137, 2, s53
	v_mov_b32_e32 v14, v1
	v_mov_b32_e32 v15, v1
	v_lshlrev_b32_e32 v16, 10, v136
	v_lshlrev_b32_e32 v17, 4, v135
	v_fma_f32 v112, v21, s12, -v130
	v_mul_f32_e32 v197, 0x3fb8aa3b, v21
	s_mov_b64 s[98:99], 0
	s_nop 0
	v_readfirstlane_b32 s100, v197
	s_nop 3
	v_mov_b32_e32 v197, s100
	ds_write_b32 v11, v10 offset:32768
	v_readfirstlane_b32 s12, v0
	ds_write_b128 v143, v[2:5]
	ds_write_b128 v143, v[6:9] offset:8192
	s_waitcnt vmcnt(0)
	v_mov_b32_e32 v0, v1
	v_mov_b32_e32 v2, v1
	v_mov_b32_e32 v3, v1
	v_mov_b32_e32 v4, v1
	v_mov_b32_e32 v5, v1
	v_mov_b32_e32 v6, v1
	v_mov_b32_e32 v7, v1
	v_mov_b32_e32 v8, v1
	v_mov_b32_e32 v9, v1
	v_mov_b32_e32 v10, v1
	v_mov_b32_e32 v11, v1
	v_mov_b32_e32 v12, v1
	v_mov_b32_e32 v13, v1
	v_mov_b64_e32 v[48:49], v[14:15]
	v_mov_b64_e32 v[64:65], v[14:15]
	v_mov_b64_e32 v[32:33], v[14:15]
	v_add3_u32 v145, 0, v16, v17
	s_add_i32 s73, s66, s49
	v_mov_b64_e32 v[46:47], v[12:13]
	v_mov_b64_e32 v[44:45], v[10:11]
	v_mov_b64_e32 v[42:43], v[8:9]
	v_mov_b64_e32 v[40:41], v[6:7]
	v_mov_b64_e32 v[38:39], v[4:5]
	v_mov_b64_e32 v[36:37], v[2:3]
	v_mov_b64_e32 v[34:35], v[0:1]
	v_mov_b64_e32 v[62:63], v[12:13]
	v_mov_b64_e32 v[60:61], v[10:11]
	v_mov_b64_e32 v[58:59], v[8:9]
	v_mov_b64_e32 v[56:57], v[6:7]
	v_mov_b64_e32 v[54:55], v[4:5]
	v_mov_b64_e32 v[52:53], v[2:3]
	v_mov_b64_e32 v[50:51], v[0:1]
	v_mov_b64_e32 v[30:31], v[12:13]
	v_mov_b64_e32 v[28:29], v[10:11]
	v_mov_b64_e32 v[26:27], v[8:9]
	v_mov_b64_e32 v[24:25], v[6:7]
	v_mov_b64_e32 v[22:23], v[4:5]
	v_mov_b64_e32 v[20:21], v[2:3]
	v_mov_b64_e32 v[18:19], v[0:1]
	v_mov_b64_e32 v[16:17], v[14:15]
	s_sub_i32 s72, s67, s28
	s_add_i32 s73, s73, 31
	v_mov_b32_e32 v113, v112
	v_mov_b32_e32 v114, v112
	v_mov_b32_e32 v115, v112
	v_mov_b32_e32 v116, v112
	v_mov_b32_e32 v117, v112
	v_mov_b32_e32 v118, v112
	v_mov_b32_e32 v119, v112
	v_mov_b32_e32 v120, v112
	v_mov_b32_e32 v121, v112
	v_mov_b32_e32 v122, v112
	v_mov_b32_e32 v123, v112
	v_mov_b32_e32 v124, v112
	v_mov_b32_e32 v125, v112
	v_mov_b32_e32 v126, v112
	v_mov_b32_e32 v127, v112
	s_lshl_b32 s75, s67, 6
	s_mov_b32 s70, 0
	v_mov_b32_e32 v148, 0
	s_mov_b64 s[62:63], 0
	v_mov_b32_e32 v150, s12
	v_mov_b64_e32 v[14:15], v[12:13]
	v_mov_b64_e32 v[12:13], v[10:11]
	v_mov_b64_e32 v[10:11], v[8:9]
	v_mov_b64_e32 v[8:9], v[6:7]
	v_mov_b64_e32 v[6:7], v[4:5]
	v_mov_b64_e32 v[4:5], v[2:3]
	v_mov_b64_e32 v[2:3], v[0:1]
	s_branch .LBB0_777

.LBB0_774:
	s_cmp_eq_u32 s48, 2
	v_fma_f32 v0, v151, s50, -v146
	v_add_f32_e32 v150, s70, v151
	s_cselect_b64 s[68:69], -1, 0
	v_cmp_lt_f32_e64 s[70:71], v0, -v131
	v_fma_f32 v196, v151, s50, -v197
	v_cmp_lt_f32_e64 s[100:101], v196, -v131
	s_nop 3
	s_or_b64 s[98:99], s[98:99], s[100:101]
	s_or_b64 s[68:69], s[68:69], s[70:71]
	s_add_i32 s48, s48, -3
	s_orn2_b64 s[68:69], s[68:69], exec
	s_mov_b32 s75, s28

; #define LAS __attribute__((address_space(3)))
; template <bool BAND>
; __device__ __forceinline__ void tile_body(f32x16* o, float& l_reg, const bf16x8* qr, const LAS unsigned char* kbs, const LAS float* wb, int vb, float ci, int hi, int keybase, int qabs) {
;     ...
; #pragma unroll
;     for (int g4 = 0; g4 < 4; ++g4) {
;         const f32x4 ba = *(const LAS f32x4*)(wb + 8 * g4 + 4 * hi) + ci, bb = *(const LAS f32x4*)(wb + 32 + 8 * g4 + 4 * hi) + ci;
; #pragma unroll
;         for (int e = 0; e < 4; ++e) { p0[4 * g4 + e] = ba[e]; p1[4 * g4 + e] = bb[e]; }
;     }
; #pragma unroll
;     for (int d0 = 0; d0 < 4; ++d0) {
;         const bf16x8 b0 = *(const LAS bf16x8*)(kbs + d0 * 2048), b1 = *(const LAS bf16x8*)(kbs + d0 * 2048 + 512);
;         p0 = __builtin_amdgcn_mfma_f32_32x32x16_bf16(b0, qr[d0], p0, 0, 0, 0); p1 = __builtin_amdgcn_mfma_f32_32x32x16_bf16(b1, qr[d0], p1, 0, 0, 0); }
.LBB0_783:
	s_andn2_saveexec_b64 s[12:13], s[12:13]
	v_mov_b32_e32 v149, s67
	v_add_f32_e32 v149, s28, v149
	v_add_f32_e32 v149, s66, v149
	s_or_b64 exec, exec, s[12:13]
	v_add_f32_e32 v149, v0, v149
	s_xor_b32 s74, s70, 1
	v_add_f32_e32 v0, v150, v149
	s_lshl_b32 s12, s74, 8
	v_sub_f32_e32 v0, v0, v140
	s_add_i32 s71, s53, s12
	s_lshl_b32 s78, s74, 14
	s_max_i32 s12, s48, 4
	v_mul_f32_e32 v140, 0x3fb8aa3b, v0
	v_lshl_add_u32 v0, v137, 2, s71
	v_readfirstlane_b32 s76, v149
	v_add_u32_e32 v149, s78, v143
	s_add_i32 s28, s12, -4
	ds_write_b32 v0, v140 offset:32768
	ds_write_b128 v149, v[66:69]
	ds_write_b128 v149, v[74:77] offset:8192
	s_lshl_b64 s[12:13], s[28:29], 11
	s_waitcnt lgkmcnt(0)
	v_lshl_add_u64 v[66:67], v[110:111], 0, s[12:13]
	s_lshl_b64 s[12:13], s[28:29], 16
	global_load_dword v140, v[66:67], off
	v_lshl_add_u64 v[74:75], v[106:107], 0, s[12:13]
	global_load_dwordx4 v[66:69], v[74:75], off
	v_cndmask_b32_e64 v74, 0, 1, s[58:59]
	v_lshl_add_u64 v[152:153], v[108:109], 0, s[12:13]
	v_cmp_ne_u32_e64 s[12:13], 1, v74
	global_load_dwordx4 v[74:77], v[152:153], off
	s_andn2_b64 vcc, exec, s[58:59]
	s_cbranch_vccnz .LBB0_792
	s_and_b64 vcc, exec, s[98:99]
	s_cbranch_vccnz .LBB0_792
	s_sub_i32 s28, s75, 64
	s_cmp_gt_i32 s28, s73
	s_cbranch_scc1 .LBB0_792
	s_lshl_b32 s64, s70, 8
	s_lshl_b32 s28, s70, 14
	s_add_i32 s66, s53, s64
	s_cmp_lt_i32 s48, s72
	v_add_u32_e32 v151, s28, v144
	s_mov_b64 s[64:65], -1
	v_add_u32_e32 v152, s28, v145
	v_lshl_add_u32 v153, v142, 2, s66
	s_cbranch_scc1 .LBB0_789
	ds_read_b128 v[34:37], v153 offset:32768
	ds_read_b128 v[38:41], v153 offset:32800
	ds_read_b128 v[42:45], v153 offset:32832
	ds_read_b128 v[46:49], v153 offset:32864
	ds_read_b128 v[50:53], v153 offset:32896
	ds_read_b128 v[54:57], v153 offset:32928
	ds_read_b128 v[58:61], v153 offset:32960
	ds_read_b128 v[62:65], v153 offset:32992
	ds_read_b128 v[154:157], v152
	ds_read_b128 v[158:161], v152 offset:512
	s_waitcnt lgkmcnt(4)
	v_pk_add_f32 v[56:57], v[118:119], v[56:57]
	s_waitcnt lgkmcnt(3)
	v_pk_add_f32 v[60:61], v[122:123], v[60:61]
	s_waitcnt lgkmcnt(2)
	v_pk_add_f32 v[64:65], v[126:127], v[64:65]
	v_pk_add_f32 v[52:53], v[114:115], v[52:53]
	v_pk_add_f32 v[62:63], v[124:125], v[62:63]
	v_pk_add_f32 v[58:59], v[120:121], v[58:59]
	v_pk_add_f32 v[54:55], v[116:117], v[54:55]
	v_pk_add_f32 v[50:51], v[112:113], v[50:51]
	v_pk_add_f32 v[48:49], v[126:127], v[48:49]
	v_pk_add_f32 v[44:45], v[122:123], v[44:45]
	v_pk_add_f32 v[40:41], v[118:119], v[40:41]
	v_pk_add_f32 v[36:37], v[114:115], v[36:37]
	v_pk_add_f32 v[46:47], v[124:125], v[46:47]
	v_pk_add_f32 v[42:43], v[120:121], v[42:43]
	v_pk_add_f32 v[38:39], v[116:117], v[38:39]
	v_pk_add_f32 v[34:35], v[112:113], v[34:35]
	s_waitcnt lgkmcnt(0)
	v_mfma_f32_32x32x16_bf16 v[50:65], v[158:161], v[94:97], v[50:65]
	v_mfma_f32_32x32x16_bf16 v[34:49], v[154:157], v[94:97], v[34:49]
	ds_read_b128 v[154:157], v152 offset:2048
	ds_read_b128 v[158:161], v152 offset:2560
	s_waitcnt lgkmcnt(0)
	v_mfma_f32_32x32x16_bf16 v[50:65], v[158:161], v[98:101], v[50:65]
	v_mfma_f32_32x32x16_bf16 v[34:49], v[154:157], v[98:101], v[34:49]
	ds_read_b128 v[154:157], v152 offset:4096
	ds_read_b128 v[158:161], v152 offset:4608
	s_waitcnt lgkmcnt(0)
	v_mfma_f32_32x32x16_bf16 v[50:65], v[158:161], v[102:105], v[50:65]
	v_mfma_f32_32x32x16_bf16 v[34:49], v[154:157], v[102:105], v[34:49]
	ds_read_b128 v[154:157], v152 offset:6656
	ds_read_b128 v[158:161], v152 offset:6144
	s_waitcnt lgkmcnt(1)
	v_mfma_f32_32x32x16_bf16 v[50:65], v[154:157], v[90:93], v[50:65]
	v_add_u32_e32 v154, s75, v142
	v_subrev_u32_e32 v156, 32, v154
	v_subrev_u32_e32 v155, 64, v154
	v_cmp_le_i32_e32 vcc, v156, v147
	s_waitcnt lgkmcnt(0)
; __device__ __forceinline__ void pv(f32x16* o, int vb, bf16x8 pa0, bf16x8 pa1, bf16x8 pa2, bf16x8 pa3) {
; #pragma unroll
;     for (int d0 = 0; d0 < 2; ++d0) { s16x4 lo[4], hi[4];
; #pragma unroll
;         for (int ks = 0; ks < 4; ++ks) {
;             asm volatile("ds_read_b64_tr_b16 %0,%1 offset:%c2" : "=&v"(lo[ks]) : "v"(vb), "i"(d0 * 4096 + ks * 1024) : "memory");
;             asm volatile("ds_read_b64_tr_b16 %0,%1 offset:%c2" : "=&v"(hi[ks]) : "v"(vb), "i"(d0 * 4096 + ks * 1024 + 512) : "memory"); }
;         asm volatile("s_waitcnt lgkmcnt(0)" ::: "memory"); __builtin_amdgcn_sched_barrier(0);
;     ...
;         o[d0] = __builtin_amdgcn_mfma_f32_32x32x16_bf16(pa0, PK(0), o[d0], 0, 0, 0);
;         o[d0] = __builtin_amdgcn_mfma_f32_32x32x16_bf16(pa1, PK(1), o[d0], 0, 0, 0);
;         o[d0] = __builtin_amdgcn_mfma_f32_32x32x16_bf16(pa2, PK(2), o[d0], 0, 0, 0);
;         o[d0] = __builtin_amdgcn_mfma_f32_32x32x16_bf16(pa3, PK(3), o[d0], 0, 0, 0);
; template <bool BAND>
; __device__ __forceinline__ void tile_body(f32x16* o, float& l_reg, const bf16x8* qr, const LAS unsigned char* kbs, const LAS float* wb, int vb, float ci, int hi, int keybase, int qabs) {
;     ...
;     if (BAND) {
; #pragma unroll
;         for (int r = 0; r < 16; ++r) { const int key = keybase + 8 * (r >> 2) + (r & 3); if (key > qabs) p0[r] = -INFINITY; if (key + 32 > qabs) p1[r] = -INFINITY; }
;     }
;     f32x2 s2 = {0.f, 0.f};
; #pragma unroll
;     for (int r = 0; r < 16; r += 2) {
;         p0[r] = __builtin_amdgcn_exp2f(p0[r]); p0[r + 1] = __builtin_amdgcn_exp2f(p0[r + 1]); p1[r] = __builtin_amdgcn_exp2f(p1[r]); p1[r + 1] = __builtin_amdgcn_exp2f(p1[r + 1]);
;         s2 += (f32x2){p0[r], p0[r + 1]}; s2 += (f32x2){p1[r], p1[r + 1]}; }
;     l_reg += s2.x + s2.y;
;     u32x4 pw0, pw1, pw2, pw3;
;     pw0 = (u32x4){cvtpk(p0[0], p0[1]), cvtpk(p0[2], p0[3]), cvtpk(p0[4], p0[5]), cvtpk(p0[6], p0[7])};
;     pw1 = (u32x4){cvtpk(p0[8], p0[9]), cvtpk(p0[10], p0[11]), cvtpk(p0[12], p0[13]), cvtpk(p0[14], p0[15])};
;     pw2 = (u32x4){cvtpk(p1[0], p1[1]), cvtpk(p1[2], p1[3]), cvtpk(p1[4], p1[5]), cvtpk(p1[6], p1[7])};
;     pw3 = (u32x4){cvtpk(p1[8], p1[9]), cvtpk(p1[10], p1[11]), cvtpk(p1[12], p1[13]), cvtpk(p1[14], p1[15])};
;     pv(o, vb, __builtin_bit_cast(bf16x8, pw0), __builtin_bit_cast(bf16x8, pw1), __builtin_bit_cast(bf16x8, pw2), __builtin_bit_cast(bf16x8, pw3));
	v_mfma_f32_32x32x16_bf16 v[34:49], v[158:161], v[90:93], v[34:49]
	s_nop 5
	v_cndmask_b32_e32 v50, v134, v50, vcc
	v_cmp_lt_i32_e32 vcc, v155, v147
	s_nop 3
	v_cndmask_b32_e32 v35, v134, v35, vcc
	v_cmp_le_i32_e32 vcc, v155, v147
	v_subrev_u32_e32 v155, 31, v154
	v_exp_f32_e32 v35, v35
	v_cndmask_b32_e32 v34, v134, v34, vcc
	v_cmp_le_i32_e32 vcc, v155, v147
	v_subrev_u32_e32 v155, 62, v154
	v_exp_f32_e32 v34, v34
	v_cndmask_b32_e32 v51, v134, v51, vcc
	v_cmp_le_i32_e32 vcc, v155, v147
	s_nop 1
	v_cndmask_b32_e32 v155, v134, v36, vcc
	v_subrev_u32_e32 v36, 30, v154
	v_cmp_le_i32_e32 vcc, v36, v147
	v_subrev_u32_e32 v36, 61, v154
	s_nop 0
	v_cndmask_b32_e32 v52, v134, v52, vcc
	v_cmp_le_i32_e32 vcc, v36, v147
	v_subrev_u32_e32 v36, 29, v154
	s_nop 0
	v_cndmask_b32_e32 v156, v134, v37, vcc
	v_cmp_le_i32_e32 vcc, v36, v147
	v_subrev_u32_e32 v36, 56, v154
	v_exp_f32_e32 v37, v51
	v_cndmask_b32_e32 v53, v134, v53, vcc
	v_cmp_le_i32_e32 vcc, v36, v147
	v_subrev_u32_e32 v36, 24, v154
	s_nop 0
	v_cndmask_b32_e32 v157, v134, v38, vcc
	v_cmp_le_i32_e32 vcc, v36, v147
	v_subrev_u32_e32 v36, 55, v154
	v_exp_f32_e32 v38, v155
	v_cndmask_b32_e32 v54, v134, v54, vcc
	v_cmp_le_i32_e32 vcc, v36, v147
	v_subrev_u32_e32 v36, 23, v154
	s_nop 0
	v_cndmask_b32_e32 v158, v134, v39, vcc
	v_cmp_le_i32_e32 vcc, v36, v147
	v_subrev_u32_e32 v36, 54, v154
	v_exp_f32_e32 v39, v156
	v_cndmask_b32_e32 v55, v134, v55, vcc
	v_cmp_le_i32_e32 vcc, v36, v147
	v_subrev_u32_e32 v36, 22, v154
	v_cvt_pk_bf16_f32 v156, v34, v35
	v_cndmask_b32_e32 v159, v134, v40, vcc
	v_cmp_le_i32_e32 vcc, v36, v147
	v_subrev_u32_e32 v36, 53, v154
	v_exp_f32_e32 v40, v52
	v_cndmask_b32_e32 v56, v134, v56, vcc
	v_cmp_le_i32_e32 vcc, v36, v147
	v_subrev_u32_e32 v36, 21, v154
	s_nop 0
	v_cndmask_b32_e32 v160, v134, v41, vcc
	v_cmp_le_i32_e32 vcc, v36, v147
	v_subrev_u32_e32 v36, 48, v154
	v_exp_f32_e32 v41, v53
	v_cndmask_b32_e32 v57, v134, v57, vcc
	v_cmp_le_i32_e32 vcc, v36, v147
	v_add_u32_e32 v36, -16, v154
	v_exp_f32_e32 v51, v57
	v_cndmask_b32_e32 v161, v134, v42, vcc
	v_cmp_le_i32_e32 vcc, v36, v147
	v_subrev_u32_e32 v36, 47, v154
	v_exp_f32_e32 v52, v161
	v_cndmask_b32_e32 v58, v134, v58, vcc
	v_cmp_le_i32_e32 vcc, v36, v147
	v_add_u32_e32 v36, -15, v154
	s_nop 0
	v_cndmask_b32_e32 v162, v134, v43, vcc
	v_cmp_le_i32_e32 vcc, v36, v147
	v_subrev_u32_e32 v36, 46, v154
	v_pk_add_f32 v[42:43], v[34:35], 0 op_sel_hi:[1,0]
	v_cndmask_b32_e32 v59, v134, v59, vcc
	v_cmp_le_i32_e32 vcc, v36, v147
	v_add_u32_e32 v36, -14, v154
	v_exp_f32_e32 v53, v162
	v_cndmask_b32_e32 v163, v134, v44, vcc
	v_cmp_le_i32_e32 vcc, v36, v147
	v_subrev_u32_e32 v36, 45, v154
	v_exp_f32_e32 v44, v157
	v_cndmask_b32_e32 v60, v134, v60, vcc
	v_cmp_le_i32_e32 vcc, v36, v147
	v_add_u32_e32 v36, -13, v154
	v_cvt_pk_bf16_f32 v157, v38, v39
	v_cndmask_b32_e32 v164, v134, v45, vcc
	v_cmp_le_i32_e32 vcc, v36, v147
	v_subrev_u32_e32 v36, 40, v154
	v_exp_f32_e32 v45, v158
	v_cndmask_b32_e32 v61, v134, v61, vcc
	v_cmp_le_i32_e32 vcc, v36, v147
	v_add_u32_e32 v36, -8, v154
	v_exp_f32_e32 v57, v164
	v_cndmask_b32_e32 v165, v134, v46, vcc
	v_cmp_le_i32_e32 vcc, v36, v147
	v_subrev_u32_e32 v36, 39, v154
	v_exp_f32_e32 v46, v54
	v_cndmask_b32_e32 v62, v134, v62, vcc
	v_cmp_le_i32_e32 vcc, v36, v147
	v_add_u32_e32 v36, -7, v154
	v_exp_f32_e32 v54, v58
	v_cndmask_b32_e32 v166, v134, v47, vcc
	v_cmp_le_i32_e32 vcc, v36, v147
	v_subrev_u32_e32 v36, 38, v154
	v_exp_f32_e32 v47, v55
	v_cndmask_b32_e32 v63, v134, v63, vcc
	v_cmp_le_i32_e32 vcc, v36, v147
	v_add_u32_e32 v36, -6, v154
	v_exp_f32_e32 v55, v59
	v_cndmask_b32_e32 v167, v134, v48, vcc
	v_cmp_le_i32_e32 vcc, v36, v147
	v_subrev_u32_e32 v36, 37, v154
	v_exp_f32_e32 v48, v159
	v_cndmask_b32_e32 v168, v134, v64, vcc
	v_cmp_le_i32_e32 vcc, v36, v147
	v_add_u32_e32 v36, -5, v154
	v_exp_f32_e32 v58, v60
	v_cndmask_b32_e32 v169, v134, v49, vcc
	v_cmp_le_i32_e32 vcc, v36, v147
	v_exp_f32_e32 v36, v50
	v_exp_f32_e32 v49, v160
	v_exp_f32_e32 v50, v56
	v_exp_f32_e32 v56, v163
	v_pk_add_f32 v[42:43], v[36:37], v[42:43]
	v_exp_f32_e32 v59, v61
	v_pk_add_f32 v[42:43], v[38:39], v[42:43]
	v_exp_f32_e32 v64, v167
	v_pk_add_f32 v[42:43], v[40:41], v[42:43]
	v_cvt_pk_bf16_f32 v167, v50, v51
	v_pk_add_f32 v[42:43], v[44:45], v[42:43]
	v_exp_f32_e32 v60, v165
	v_pk_add_f32 v[42:43], v[46:47], v[42:43]
	v_exp_f32_e32 v61, v166
	v_pk_add_f32 v[42:43], v[48:49], v[42:43]
	v_cvt_pk_bf16_f32 v160, v52, v53
	v_pk_add_f32 v[42:43], v[50:51], v[42:43]
	ds_read_b64_tr_b16 v[50:51],v151 offset:0
	v_exp_f32_e32 v62, v62
	v_pk_add_f32 v[42:43], v[52:53], v[42:43]
	ds_read_b64_tr_b16 v[52:53],v151 offset:512
	v_exp_f32_e32 v63, v63
	v_pk_add_f32 v[42:43], v[54:55], v[42:43]
	v_exp_f32_e32 v172, v168
	v_cvt_pk_bf16_f32 v168, v54, v55
	ds_read_b64_tr_b16 v[54:55],v151 offset:1024
	v_cndmask_b32_e32 v154, v134, v65, vcc
	v_pk_add_f32 v[42:43], v[56:57], v[42:43]
	v_exp_f32_e32 v65, v169
	v_cvt_pk_bf16_f32 v161, v56, v57
	ds_read_b64_tr_b16 v[56:57],v151 offset:1536
	v_pk_add_f32 v[42:43], v[58:59], v[42:43]
	v_exp_f32_e32 v173, v154
	v_cvt_pk_bf16_f32 v169, v58, v59
	ds_read_b64_tr_b16 v[58:59],v151 offset:2048
	v_pk_add_f32 v[42:43], v[60:61], v[42:43]
	v_cvt_pk_bf16_f32 v162, v60, v61
	ds_read_b64_tr_b16 v[60:61],v151 offset:2560
	v_pk_add_f32 v[42:43], v[62:63], v[42:43]
	v_cvt_pk_bf16_f32 v170, v62, v63
	ds_read_b64_tr_b16 v[62:63],v151 offset:3072
	v_pk_add_f32 v[42:43], v[64:65], v[42:43]
	v_cvt_pk_bf16_f32 v163, v64, v65
	ds_read_b64_tr_b16 v[64:65],v151 offset:3584
	v_pk_add_f32 v[42:43], v[172:173], v[42:43]
	s_waitcnt lgkmcnt(0)
	v_cvt_pk_bf16_f32 v158, v44, v45
	v_add_f32_e32 v42, v42, v43
	v_add_f32_e32 v154, v148, v42
	v_cvt_pk_bf16_f32 v159, v48, v49
	v_cvt_pk_bf16_f32 v164, v36, v37
	v_cvt_pk_bf16_f32 v165, v40, v41
	v_cvt_pk_bf16_f32 v166, v46, v47
	v_cvt_pk_bf16_f32 v171, v172, v173
	v_mfma_f32_32x32x16_bf16 v[2:17], v[156:159], v[50:53], v[2:17]
	ds_read_b64_tr_b16 v[172:173],v151 offset:4096
	ds_read_b64_tr_b16 v[174:175],v151 offset:4608
	ds_read_b64_tr_b16 v[176:177],v151 offset:5120
	ds_read_b64_tr_b16 v[178:179],v151 offset:5632
	ds_read_b64_tr_b16 v[180:181],v151 offset:6144
	ds_read_b64_tr_b16 v[182:183],v151 offset:6656
	ds_read_b64_tr_b16 v[184:185],v151 offset:7168
	v_mfma_f32_32x32x16_bf16 v[2:17], v[160:163], v[54:57], v[2:17]
	ds_read_b64_tr_b16 v[186:187],v151 offset:7680
	s_waitcnt lgkmcnt(0)
	v_mfma_f32_32x32x16_bf16 v[2:17], v[164:167], v[58:61], v[2:17]
	v_mfma_f32_32x32x16_bf16 v[2:17], v[168:171], v[62:65], v[2:17]
	v_mfma_f32_32x32x16_bf16 v[18:33], v[156:159], v[172:175], v[18:33]
	s_mov_b64 s[64:65], 0
	v_mfma_f32_32x32x16_bf16 v[18:33], v[160:163], v[176:179], v[18:33]
	v_mfma_f32_32x32x16_bf16 v[18:33], v[164:167], v[180:183], v[18:33]
	v_mfma_f32_32x32x16_bf16 v[18:33], v[168:171], v[184:187], v[18:33]

; __device__ __forceinline__ void attn_unit(const UnitDesc& u, LAS unsigned char* shm, float qkmax, float thresh) {
;     ...
;     for (;;) {
;         ATT_ITER(kA, vA, lA); if (stop) break;
.LBB0_792:
	s_cmp_lg_u32 s48, 0
	v_fma_f32 v151, v150, s50, -v146
	s_cselect_b64 s[64:65], -1, 0
	v_cmp_nlt_f32_e64 s[66:67], v151, -v131
	v_fma_f32 v196, v150, s50, -v197
	v_cmp_lt_f32_e64 s[100:101], v196, -v131
	s_nop 3
	s_or_b64 s[98:99], s[98:99], s[100:101]
	s_and_b64 s[68:69], s[64:65], s[66:67]
	s_mov_b64 s[66:67], -1
	s_and_saveexec_b64 s[64:65], s[68:69]
	s_cbranch_execz .LBB0_776
	s_waitcnt lgkmcnt(0)
	s_barrier
	s_waitcnt vmcnt(6)
	s_nop 1
	v_add_f32_dpp v151, v141, v141 row_shl:1 row_mask:0xf bank_mask:0xf bound_ctrl:1
	s_nop 1
	v_add_f32_dpp v151, v151, v151 row_shl:2 row_mask:0xf bank_mask:0xf bound_ctrl:1
	s_nop 1
	v_add_f32_dpp v151, v151, v151 row_shl:4 row_mask:0xf bank_mask:0xf bound_ctrl:1
	s_nop 1
	v_add_f32_dpp v152, v151, v151 row_shl:8 row_mask:0xf bank_mask:0xf bound_ctrl:1
	s_nop 0
	v_readlane_b32 s28, v152, 16
	v_readlane_b32 s79, v152, 32
	v_readlane_b32 s77, v152, 48
	s_and_saveexec_b64 s[66:67], s[6:7]
	s_xor_b64 s[66:67], exec, s[66:67]
	s_cbranch_execz .LBB0_799
	s_and_saveexec_b64 s[68:69], s[8:9]
	s_xor_b64 s[68:69], exec, s[68:69]
	v_mov_b32_e32 v151, s77
	v_cndmask_b32_e64 v153, 0, v151, s[10:11]
	s_andn2_saveexec_b64 s[68:69], s[68:69]
	v_mov_b32_e32 v151, s77
	v_add_f32_e32 v153, s79, v151
	s_or_b64 exec, exec, s[68:69]
.LBB0_799:
	s_andn2_saveexec_b64 s[66:67], s[66:67]
	v_mov_b32_e32 v151, s79
	v_add_f32_e32 v151, s28, v151
	v_add_f32_e32 v153, s77, v151
	s_or_b64 exec, exec, s[66:67]
	v_add_f32_e32 v151, s76, v150
	v_add_f32_e32 v150, v152, v153
	v_add_f32_e32 v152, v151, v150
	s_lshl_b32 s28, s70, 8
	v_sub_f32_e32 v141, v152, v141
	s_add_i32 s76, s53, s28
	v_mul_f32_e32 v141, 0x3fb8aa3b, v141
	v_lshl_add_u32 v152, v137, 2, s76
	s_lshl_b32 s77, s70, 14
	ds_write_b32 v152, v141 offset:32768
	v_add_u32_e32 v141, s77, v143
	s_max_i32 s28, s48, 5
	ds_write_b128 v141, v[70:73]
	ds_write_b128 v141, v[82:85] offset:8192
	s_add_i32 s28, s28, -5
	s_waitcnt lgkmcnt(0)
	s_lshl_b64 s[66:67], s[28:29], 11
	v_lshl_add_u64 v[70:71], v[110:111], 0, s[66:67]
	global_load_dword v141, v[70:71], off
	s_lshl_b64 s[66:67], s[28:29], 16
	v_lshl_add_u64 v[82:83], v[106:107], 0, s[66:67]
	global_load_dwordx4 v[70:73], v[82:83], off
	v_lshl_add_u64 v[152:153], v[108:109], 0, s[66:67]
	global_load_dwordx4 v[82:85], v[152:153], off
	v_readfirstlane_b32 s79, v150
	s_and_b64 vcc, exec, s[12:13]
	s_cbranch_vccnz .LBB0_808
	s_and_b64 vcc, exec, s[98:99]
	s_cbranch_vccnz .LBB0_808
	s_add_i32 s28, s75, 0xffffff80
	s_cmp_gt_i32 s28, s73
	s_cbranch_scc1 .LBB0_808
	s_cmp_le_i32 s48, s72
	v_add_u32_e32 v150, s78, v144
	s_mov_b64 s[66:67], -1
	v_add_u32_e32 v152, s78, v145
	v_lshl_add_u32 v153, v142, 2, s71
	s_cbranch_scc0 .LBB0_805
; #define LAS __attribute__((address_space(3)))
; __device__ __forceinline__ void pv(f32x16* o, int vb, bf16x8 pa0, bf16x8 pa1, bf16x8 pa2, bf16x8 pa3) {
; #pragma unroll
;     for (int d0 = 0; d0 < 2; ++d0) { s16x4 lo[4], hi[4];
; #pragma unroll
;         for (int ks = 0; ks < 4; ++ks) {
; template <bool BAND>
; __device__ __forceinline__ void tile_body(f32x16* o, float& l_reg, const bf16x8* qr, const LAS unsigned char* kbs, const LAS float* wb, int vb, float ci, int hi, int keybase, int qabs) {
;     ...
; #pragma unroll
;     for (int g4 = 0; g4 < 4; ++g4) {
;         const f32x4 ba = *(const LAS f32x4*)(wb + 8 * g4 + 4 * hi) + ci, bb = *(const LAS f32x4*)(wb + 32 + 8 * g4 + 4 * hi) + ci;
; #pragma unroll
;         for (int e = 0; e < 4; ++e) { p0[4 * g4 + e] = ba[e]; p1[4 * g4 + e] = bb[e]; }
;     }
; #pragma unroll
;     for (int d0 = 0; d0 < 4; ++d0) {
;         const bf16x8 b0 = *(const LAS bf16x8*)(kbs + d0 * 2048), b1 = *(const LAS bf16x8*)(kbs + d0 * 2048 + 512);
;         p0 = __builtin_amdgcn_mfma_f32_32x32x16_bf16(b0, qr[d0], p0, 0, 0, 0); p1 = __builtin_amdgcn_mfma_f32_32x32x16_bf16(b1, qr[d0], p1, 0, 0, 0); }
;     if (BAND) {
; #pragma unroll
;         for (int r = 0; r < 16; ++r) { const int key = keybase + 8 * (r >> 2) + (r & 3); if (key > qabs) p0[r] = -INFINITY; if (key + 32 > qabs) p1[r] = -INFINITY; }
;     }
;     f32x2 s2 = {0.f, 0.f};
; #pragma unroll
;     for (int r = 0; r < 16; r += 2) {
;         p0[r] = __builtin_amdgcn_exp2f(p0[r]); p0[r + 1] = __builtin_amdgcn_exp2f(p0[r + 1]); p1[r] = __builtin_amdgcn_exp2f(p1[r]); p1[r + 1] = __builtin_amdgcn_exp2f(p1[r + 1]);
;         s2 += (f32x2){p0[r], p0[r + 1]}; s2 += (f32x2){p1[r], p1[r + 1]}; }
;     l_reg += s2.x + s2.y;
;     u32x4 pw0, pw1, pw2, pw3;
;     pw0 = (u32x4){cvtpk(p0[0], p0[1]), cvtpk(p0[2], p0[3]), cvtpk(p0[4], p0[5]), cvtpk(p0[6], p0[7])};
;     pw1 = (u32x4){cvtpk(p0[8], p0[9]), cvtpk(p0[10], p0[11]), cvtpk(p0[12], p0[13]), cvtpk(p0[14], p0[15])};
;     pw2 = (u32x4){cvtpk(p1[0], p1[1]), cvtpk(p1[2], p1[3]), cvtpk(p1[4], p1[5]), cvtpk(p1[6], p1[7])};
;     pw3 = (u32x4){cvtpk(p1[8], p1[9]), cvtpk(p1[10], p1[11]), cvtpk(p1[12], p1[13]), cvtpk(p1[14], p1[15])};
;     pv(o, vb, __builtin_bit_cast(bf16x8, pw0), __builtin_bit_cast(bf16x8, pw1), __builtin_bit_cast(bf16x8, pw2), __builtin_bit_cast(bf16x8, pw3));
	ds_read_b128 v[34:37], v153 offset:32768
	ds_read_b128 v[38:41], v153 offset:32800
	ds_read_b128 v[42:45], v153 offset:32832
	ds_read_b128 v[46:49], v153 offset:32864
	ds_read_b128 v[50:53], v153 offset:32896
	ds_read_b128 v[54:57], v153 offset:32928
	ds_read_b128 v[58:61], v153 offset:32960
	ds_read_b128 v[62:65], v153 offset:32992
	ds_read_b128 v[154:157], v152
	ds_read_b128 v[158:161], v152 offset:512
	s_waitcnt lgkmcnt(6)
	v_pk_add_f32 v[48:49], v[126:127], v[48:49]
	v_pk_add_f32 v[44:45], v[122:123], v[44:45]
	v_pk_add_f32 v[40:41], v[118:119], v[40:41]
	v_pk_add_f32 v[36:37], v[114:115], v[36:37]
	v_pk_add_f32 v[46:47], v[124:125], v[46:47]
	v_pk_add_f32 v[42:43], v[120:121], v[42:43]
	v_pk_add_f32 v[38:39], v[116:117], v[38:39]
	v_pk_add_f32 v[34:35], v[112:113], v[34:35]
	s_waitcnt lgkmcnt(2)
	v_pk_add_f32 v[64:65], v[126:127], v[64:65]
	v_pk_add_f32 v[60:61], v[122:123], v[60:61]
	s_waitcnt lgkmcnt(1)
	v_mfma_f32_32x32x16_bf16 v[34:49], v[154:157], v[94:97], v[34:49]
	v_add_f32_e64 v56, v118, v56
	v_add_f32_e64 v57, v119, v57
	v_add_f32_e64 v52, v114, v52
	v_add_f32_e64 v53, v115, v53
	v_add_f32_e64 v62, v124, v62
	v_add_f32_e64 v63, v125, v63
	v_pk_add_f32 v[58:59], v[120:121], v[58:59]
	v_pk_add_f32 v[54:55], v[116:117], v[54:55]
	v_pk_add_f32 v[50:51], v[112:113], v[50:51]
	s_waitcnt lgkmcnt(0)
	s_nop 0
	v_mfma_f32_32x32x16_bf16 v[50:65], v[158:161], v[94:97], v[50:65]
	ds_read_b128 v[154:157], v152 offset:2048
	ds_read_b128 v[158:161], v152 offset:2560
	s_waitcnt lgkmcnt(1)
	v_mfma_f32_32x32x16_bf16 v[34:49], v[154:157], v[98:101], v[34:49]
	s_waitcnt lgkmcnt(0)
	v_mfma_f32_32x32x16_bf16 v[50:65], v[158:161], v[98:101], v[50:65]
	ds_read_b128 v[154:157], v152 offset:4096
	ds_read_b128 v[158:161], v152 offset:4608
	s_waitcnt lgkmcnt(1)
	v_mfma_f32_32x32x16_bf16 v[34:49], v[154:157], v[102:105], v[34:49]
	s_waitcnt lgkmcnt(0)
	v_mfma_f32_32x32x16_bf16 v[50:65], v[158:161], v[102:105], v[50:65]
	ds_read_b128 v[154:157], v152 offset:6144
	ds_read_b128 v[158:161], v152 offset:6656
	s_waitcnt lgkmcnt(1)
	v_mfma_f32_32x32x16_bf16 v[34:49], v[154:157], v[90:93], v[34:49]
	s_waitcnt lgkmcnt(0)
	v_mfma_f32_32x32x16_bf16 v[50:65], v[158:161], v[90:93], v[50:65]
	s_nop 9
	v_exp_f32_e32 v34, v34
	v_exp_f32_e32 v35, v35
	v_exp_f32_e32 v36, v36
	v_exp_f32_e32 v37, v37
	v_exp_f32_e32 v38, v38
	v_pk_add_f32 v[154:155], v[34:35], 0 op_sel_hi:[1,0]
	v_exp_f32_e32 v39, v39
	v_exp_f32_e32 v50, v50
	v_exp_f32_e32 v51, v51
	v_exp_f32_e32 v52, v52
	v_exp_f32_e32 v53, v53
	v_exp_f32_e32 v54, v54
	v_pk_add_f32 v[154:155], v[50:51], v[154:155]
	v_exp_f32_e32 v55, v55
	v_pk_add_f32 v[154:155], v[36:37], v[154:155]
	v_exp_f32_e32 v40, v40
	v_exp_f32_e32 v41, v41
	v_pk_add_f32 v[154:155], v[52:53], v[154:155]
	v_exp_f32_e32 v56, v56
	v_exp_f32_e32 v57, v57
	v_pk_add_f32 v[154:155], v[38:39], v[154:155]
	v_exp_f32_e32 v42, v42
	v_exp_f32_e32 v43, v43
	v_pk_add_f32 v[154:155], v[54:55], v[154:155]
	v_exp_f32_e32 v58, v58
	v_exp_f32_e32 v59, v59
	v_pk_add_f32 v[154:155], v[40:41], v[154:155]
	v_exp_f32_e32 v44, v44
	v_exp_f32_e32 v45, v45
	v_pk_add_f32 v[154:155], v[56:57], v[154:155]
	v_exp_f32_e32 v60, v60
	v_exp_f32_e32 v61, v61
	v_pk_add_f32 v[154:155], v[42:43], v[154:155]
	v_exp_f32_e32 v46, v46
	v_exp_f32_e32 v47, v47
	v_cvt_pk_bf16_f32 v164, v50, v51
	ds_read_b64_tr_b16 v[50:51],v150 offset:0
	v_pk_add_f32 v[154:155], v[58:59], v[154:155]
	v_exp_f32_e32 v62, v62
	v_exp_f32_e32 v63, v63
	v_cvt_pk_bf16_f32 v165, v52, v53
	ds_read_b64_tr_b16 v[52:53],v150 offset:512
	v_pk_add_f32 v[154:155], v[44:45], v[154:155]
	v_exp_f32_e32 v48, v48
	v_exp_f32_e32 v49, v49
	v_cvt_pk_bf16_f32 v166, v54, v55
	ds_read_b64_tr_b16 v[54:55],v150 offset:1024
	v_pk_add_f32 v[154:155], v[60:61], v[154:155]
	v_exp_f32_e32 v64, v64
	v_exp_f32_e32 v65, v65
	v_cvt_pk_bf16_f32 v167, v56, v57
	ds_read_b64_tr_b16 v[56:57],v150 offset:1536
	v_pk_add_f32 v[154:155], v[46:47], v[154:155]
	v_cvt_pk_bf16_f32 v168, v58, v59
	ds_read_b64_tr_b16 v[58:59],v150 offset:2048
	v_pk_add_f32 v[154:155], v[62:63], v[154:155]
	v_cvt_pk_bf16_f32 v169, v60, v61
	ds_read_b64_tr_b16 v[60:61],v150 offset:2560
	v_pk_add_f32 v[154:155], v[48:49], v[154:155]
	v_cvt_pk_bf16_f32 v170, v62, v63
	ds_read_b64_tr_b16 v[62:63],v150 offset:3072
	v_pk_add_f32 v[154:155], v[64:65], v[154:155]
	v_cvt_pk_bf16_f32 v171, v64, v65
	ds_read_b64_tr_b16 v[64:65],v150 offset:3584
	s_waitcnt lgkmcnt(0)
	v_add_f32_e32 v154, v154, v155
	v_add_f32_e32 v154, v148, v154
	v_cvt_pk_bf16_f32 v156, v34, v35
	v_cvt_pk_bf16_f32 v157, v36, v37
	v_cvt_pk_bf16_f32 v158, v38, v39
	v_cvt_pk_bf16_f32 v159, v40, v41
	v_cvt_pk_bf16_f32 v160, v42, v43
	v_cvt_pk_bf16_f32 v161, v44, v45
	v_cvt_pk_bf16_f32 v162, v46, v47
	v_cvt_pk_bf16_f32 v163, v48, v49
	v_mfma_f32_32x32x16_bf16 v[2:17], v[156:159], v[50:53], v[2:17]
	ds_read_b64_tr_b16 v[172:173],v150 offset:4096
	ds_read_b64_tr_b16 v[174:175],v150 offset:4608
	ds_read_b64_tr_b16 v[176:177],v150 offset:5120
	ds_read_b64_tr_b16 v[178:179],v150 offset:5632
	ds_read_b64_tr_b16 v[180:181],v150 offset:6144
	ds_read_b64_tr_b16 v[182:183],v150 offset:6656
	ds_read_b64_tr_b16 v[184:185],v150 offset:7168
	s_nop 0
	v_mfma_f32_32x32x16_bf16 v[2:17], v[160:163], v[54:57], v[2:17]
	ds_read_b64_tr_b16 v[186:187],v150 offset:7680
	s_waitcnt lgkmcnt(0)
	v_mfma_f32_32x32x16_bf16 v[2:17], v[164:167], v[58:61], v[2:17]
	v_mfma_f32_32x32x16_bf16 v[2:17], v[168:171], v[62:65], v[2:17]
	v_mfma_f32_32x32x16_bf16 v[18:33], v[156:159], v[172:175], v[18:33]
	s_mov_b64 s[66:67], 0
	v_mfma_f32_32x32x16_bf16 v[18:33], v[160:163], v[176:179], v[18:33]
	v_mfma_f32_32x32x16_bf16 v[18:33], v[164:167], v[180:183], v[18:33]
	v_mfma_f32_32x32x16_bf16 v[18:33], v[168:171], v[184:187], v[18:33]

; __device__ __forceinline__ void attn_unit(const UnitDesc& u, LAS unsigned char* shm, float qkmax, float thresh) {
;     ...
;     for (;;) {
;         ATT_ITER(kA, vA, lA); if (stop) break;
;         ATT_ITER(kB, vB, lB); if (stop) break;
.LBB0_808:
	s_cmp_lg_u32 s48, 1
	v_fma_f32 v150, v151, s50, -v146
	s_cselect_b64 s[66:67], -1, 0
	v_cmp_nlt_f32_e64 s[68:69], v150, -v131
	v_fma_f32 v196, v151, s50, -v197
	v_cmp_lt_f32_e64 s[100:101], v196, -v131
	s_nop 3
	s_or_b64 s[98:99], s[98:99], s[100:101]
	s_and_b64 s[70:71], s[66:67], s[68:69]
	s_mov_b64 s[68:69], -1
	s_and_saveexec_b64 s[66:67], s[70:71]
	s_cbranch_execz .LBB0_775
	s_waitcnt lgkmcnt(0)
	s_barrier
	s_waitcnt vmcnt(6)
	s_nop 1
	v_add_f32_dpp v150, v139, v139 row_shl:1 row_mask:0xf bank_mask:0xf bound_ctrl:1
	s_nop 1
	v_add_f32_dpp v150, v150, v150 row_shl:2 row_mask:0xf bank_mask:0xf bound_ctrl:1
	s_nop 1
	v_add_f32_dpp v150, v150, v150 row_shl:4 row_mask:0xf bank_mask:0xf bound_ctrl:1
	s_nop 1
	v_add_f32_dpp v150, v150, v150 row_shl:8 row_mask:0xf bank_mask:0xf bound_ctrl:1
	s_nop 0
	v_readlane_b32 s28, v150, 16
	v_readlane_b32 s80, v150, 32
	v_readlane_b32 s78, v150, 48
	s_and_saveexec_b64 s[68:69], s[6:7]
	s_xor_b64 s[68:69], exec, s[68:69]
	s_cbranch_execz .LBB0_815
	s_and_saveexec_b64 s[70:71], s[8:9]
	s_xor_b64 s[70:71], exec, s[70:71]
	v_mov_b32_e32 v152, s78
	v_cndmask_b32_e64 v152, 0, v152, s[10:11]
	s_andn2_saveexec_b64 s[70:71], s[70:71]
	v_mov_b32_e32 v152, s78
	v_add_f32_e32 v152, s80, v152
	s_or_b64 exec, exec, s[70:71]

; #define LAS __attribute__((address_space(3)))
; template <bool BAND>
; __device__ __forceinline__ void tile_body(f32x16* o, float& l_reg, const bf16x8* qr, const LAS unsigned char* kbs, const LAS float* wb, int vb, float ci, int hi, int keybase, int qabs) {
;     ...
; #pragma unroll
;     for (int g4 = 0; g4 < 4; ++g4) {
;         const f32x4 ba = *(const LAS f32x4*)(wb + 8 * g4 + 4 * hi) + ci, bb = *(const LAS f32x4*)(wb + 32 + 8 * g4 + 4 * hi) + ci;
; #pragma unroll
;         for (int e = 0; e < 4; ++e) { p0[4 * g4 + e] = ba[e]; p1[4 * g4 + e] = bb[e]; }
;     }
; #pragma unroll
;     for (int d0 = 0; d0 < 4; ++d0) {
;         const bf16x8 b0 = *(const LAS bf16x8*)(kbs + d0 * 2048), b1 = *(const LAS bf16x8*)(kbs + d0 * 2048 + 512);
;         p0 = __builtin_amdgcn_mfma_f32_32x32x16_bf16(b0, qr[d0], p0, 0, 0, 0); p1 = __builtin_amdgcn_mfma_f32_32x32x16_bf16(b1, qr[d0], p1, 0, 0, 0); }
;     if (BAND) {
; #pragma unroll
;         for (int r = 0; r < 16; ++r) { const int key = keybase + 8 * (r >> 2) + (r & 3); if (key > qabs) p0[r] = -INFINITY; if (key + 32 > qabs) p1[r] = -INFINITY; }
.LBB0_819:
	s_andn2_b64 vcc, exec, s[68:69]
	s_cbranch_vccnz .LBB0_774
	s_and_b64 vcc, exec, s[98:99]
	s_cbranch_vccnz .LBB0_774
	s_add_i32 s28, s75, 0xffffff40
	s_cmp_gt_i32 s28, s73
	s_cbranch_scc1 .LBB0_774
	s_add_i32 s68, s48, -2
	s_cmp_lt_i32 s68, s72
	v_add_u32_e32 v0, s77, v144
	s_mov_b64 s[68:69], -1
	v_add_u32_e32 v149, s77, v145
	v_lshl_add_u32 v150, v142, 2, s76
	s_cbranch_scc1 .LBB0_823
	ds_read_b128 v[34:37], v150 offset:32768
	ds_read_b128 v[38:41], v150 offset:32800
	ds_read_b128 v[42:45], v150 offset:32832
	ds_read_b128 v[46:49], v150 offset:32864
	ds_read_b128 v[50:53], v150 offset:32896
	ds_read_b128 v[54:57], v150 offset:32928
	ds_read_b128 v[58:61], v150 offset:32960
	ds_read_b128 v[62:65], v150 offset:32992
	ds_read_b128 v[152:155], v149
	ds_read_b128 v[156:159], v149 offset:512
	s_waitcnt lgkmcnt(4)
	v_pk_add_f32 v[56:57], v[118:119], v[56:57]
	s_waitcnt lgkmcnt(3)
	v_pk_add_f32 v[60:61], v[122:123], v[60:61]
	s_waitcnt lgkmcnt(2)
	v_pk_add_f32 v[64:65], v[126:127], v[64:65]
	v_pk_add_f32 v[52:53], v[114:115], v[52:53]
	v_pk_add_f32 v[62:63], v[124:125], v[62:63]
	v_pk_add_f32 v[58:59], v[120:121], v[58:59]
	v_pk_add_f32 v[54:55], v[116:117], v[54:55]
	v_pk_add_f32 v[50:51], v[112:113], v[50:51]
	v_pk_add_f32 v[48:49], v[126:127], v[48:49]
	v_pk_add_f32 v[44:45], v[122:123], v[44:45]
	v_pk_add_f32 v[40:41], v[118:119], v[40:41]
	v_pk_add_f32 v[36:37], v[114:115], v[36:37]
	v_pk_add_f32 v[46:47], v[124:125], v[46:47]
	v_pk_add_f32 v[42:43], v[120:121], v[42:43]
	v_pk_add_f32 v[38:39], v[116:117], v[38:39]
	v_pk_add_f32 v[34:35], v[112:113], v[34:35]
	s_waitcnt lgkmcnt(0)
	v_mfma_f32_32x32x16_bf16 v[50:65], v[156:159], v[94:97], v[50:65]
	v_mfma_f32_32x32x16_bf16 v[34:49], v[152:155], v[94:97], v[34:49]
	ds_read_b128 v[152:155], v149 offset:2048
	ds_read_b128 v[156:159], v149 offset:2560
	s_waitcnt lgkmcnt(0)
	v_mfma_f32_32x32x16_bf16 v[50:65], v[156:159], v[98:101], v[50:65]
	v_mfma_f32_32x32x16_bf16 v[34:49], v[152:155], v[98:101], v[34:49]
	ds_read_b128 v[152:155], v149 offset:4096
	ds_read_b128 v[156:159], v149 offset:4608
	s_waitcnt lgkmcnt(0)
	v_mfma_f32_32x32x16_bf16 v[50:65], v[156:159], v[102:105], v[50:65]
	v_mfma_f32_32x32x16_bf16 v[34:49], v[152:155], v[102:105], v[34:49]
	ds_read_b128 v[152:155], v149 offset:6656
	ds_read_b128 v[156:159], v149 offset:6144
	s_waitcnt lgkmcnt(1)
	v_mfma_f32_32x32x16_bf16 v[50:65], v[152:155], v[90:93], v[50:65]
	v_add_u32_e32 v152, s75, v142
	v_add_u32_e32 v154, 0xffffff60, v152
	v_add_u32_e32 v153, 0xffffff40, v152
	v_cmp_le_i32_e32 vcc, v154, v147
	s_waitcnt lgkmcnt(0)
; __device__ __forceinline__ void pv(f32x16* o, int vb, bf16x8 pa0, bf16x8 pa1, bf16x8 pa2, bf16x8 pa3) {
; #pragma unroll
;     for (int d0 = 0; d0 < 2; ++d0) { s16x4 lo[4], hi[4];
; #pragma unroll
;         for (int ks = 0; ks < 4; ++ks) {
;             asm volatile("ds_read_b64_tr_b16 %0,%1 offset:%c2" : "=&v"(lo[ks]) : "v"(vb), "i"(d0 * 4096 + ks * 1024) : "memory");
;             asm volatile("ds_read_b64_tr_b16 %0,%1 offset:%c2" : "=&v"(hi[ks]) : "v"(vb), "i"(d0 * 4096 + ks * 1024 + 512) : "memory"); }
;         asm volatile("s_waitcnt lgkmcnt(0)" ::: "memory"); __builtin_amdgcn_sched_barrier(0);
;     ...
;         o[d0] = __builtin_amdgcn_mfma_f32_32x32x16_bf16(pa0, PK(0), o[d0], 0, 0, 0);
;         o[d0] = __builtin_amdgcn_mfma_f32_32x32x16_bf16(pa1, PK(1), o[d0], 0, 0, 0);
;         o[d0] = __builtin_amdgcn_mfma_f32_32x32x16_bf16(pa2, PK(2), o[d0], 0, 0, 0);
;         o[d0] = __builtin_amdgcn_mfma_f32_32x32x16_bf16(pa3, PK(3), o[d0], 0, 0, 0);
; template <bool BAND>
; __device__ __forceinline__ void tile_body(f32x16* o, float& l_reg, const bf16x8* qr, const LAS unsigned char* kbs, const LAS float* wb, int vb, float ci, int hi, int keybase, int qabs) {
;     ...
;         for (int r = 0; r < 16; ++r) { const int key = keybase + 8 * (r >> 2) + (r & 3); if (key > qabs) p0[r] = -INFINITY; if (key + 32 > qabs) p1[r] = -INFINITY; }
;     }
;     f32x2 s2 = {0.f, 0.f};
; #pragma unroll
;     for (int r = 0; r < 16; r += 2) {
;         p0[r] = __builtin_amdgcn_exp2f(p0[r]); p0[r + 1] = __builtin_amdgcn_exp2f(p0[r + 1]); p1[r] = __builtin_amdgcn_exp2f(p1[r]); p1[r + 1] = __builtin_amdgcn_exp2f(p1[r + 1]);
;         s2 += (f32x2){p0[r], p0[r + 1]}; s2 += (f32x2){p1[r], p1[r + 1]}; }
;     l_reg += s2.x + s2.y;
;     u32x4 pw0, pw1, pw2, pw3;
;     pw0 = (u32x4){cvtpk(p0[0], p0[1]), cvtpk(p0[2], p0[3]), cvtpk(p0[4], p0[5]), cvtpk(p0[6], p0[7])};
;     pw1 = (u32x4){cvtpk(p0[8], p0[9]), cvtpk(p0[10], p0[11]), cvtpk(p0[12], p0[13]), cvtpk(p0[14], p0[15])};
;     pw2 = (u32x4){cvtpk(p1[0], p1[1]), cvtpk(p1[2], p1[3]), cvtpk(p1[4], p1[5]), cvtpk(p1[6], p1[7])};
;     pw3 = (u32x4){cvtpk(p1[8], p1[9]), cvtpk(p1[10], p1[11]), cvtpk(p1[12], p1[13]), cvtpk(p1[14], p1[15])};
;     pv(o, vb, __builtin_bit_cast(bf16x8, pw0), __builtin_bit_cast(bf16x8, pw1), __builtin_bit_cast(bf16x8, pw2), __builtin_bit_cast(bf16x8, pw3));
	v_mfma_f32_32x32x16_bf16 v[34:49], v[156:159], v[90:93], v[34:49]
	s_nop 5
	v_cndmask_b32_e32 v50, v134, v50, vcc
	v_cmp_lt_i32_e32 vcc, v153, v147
	s_nop 3
	v_cndmask_b32_e32 v35, v134, v35, vcc
	v_cmp_le_i32_e32 vcc, v153, v147
	v_add_u32_e32 v153, 0xffffff61, v152
	v_exp_f32_e32 v35, v35
	v_cndmask_b32_e32 v34, v134, v34, vcc
	v_cmp_le_i32_e32 vcc, v153, v147
	v_add_u32_e32 v153, 0xffffff42, v152
	v_exp_f32_e32 v34, v34
	v_cndmask_b32_e32 v51, v134, v51, vcc
	v_cmp_le_i32_e32 vcc, v153, v147
	s_nop 1
	v_cndmask_b32_e32 v153, v134, v36, vcc
	v_add_u32_e32 v36, 0xffffff62, v152
	v_cmp_le_i32_e32 vcc, v36, v147
	v_add_u32_e32 v36, 0xffffff43, v152
	s_nop 0
	v_cndmask_b32_e32 v52, v134, v52, vcc
	v_cmp_le_i32_e32 vcc, v36, v147
	v_add_u32_e32 v36, 0xffffff63, v152
	s_nop 0
	v_cndmask_b32_e32 v154, v134, v37, vcc
	v_cmp_le_i32_e32 vcc, v36, v147
	v_add_u32_e32 v36, 0xffffff48, v152
	v_exp_f32_e32 v37, v51
	v_cndmask_b32_e32 v53, v134, v53, vcc
	v_cmp_le_i32_e32 vcc, v36, v147
	v_add_u32_e32 v36, 0xffffff68, v152
	s_nop 0
	v_cndmask_b32_e32 v155, v134, v38, vcc
	v_cmp_le_i32_e32 vcc, v36, v147
	v_add_u32_e32 v36, 0xffffff49, v152
	v_exp_f32_e32 v38, v153
	v_cndmask_b32_e32 v54, v134, v54, vcc
	v_cmp_le_i32_e32 vcc, v36, v147
	v_add_u32_e32 v36, 0xffffff69, v152
	s_nop 0
	v_cndmask_b32_e32 v156, v134, v39, vcc
	v_cmp_le_i32_e32 vcc, v36, v147
	v_add_u32_e32 v36, 0xffffff4a, v152
	v_exp_f32_e32 v39, v154
	v_cndmask_b32_e32 v55, v134, v55, vcc
	v_cmp_le_i32_e32 vcc, v36, v147
	v_add_u32_e32 v36, 0xffffff6a, v152
	v_cvt_pk_bf16_f32 v154, v34, v35
	v_cndmask_b32_e32 v157, v134, v40, vcc
	v_cmp_le_i32_e32 vcc, v36, v147
	v_add_u32_e32 v36, 0xffffff4b, v152
	v_exp_f32_e32 v40, v52
	v_cndmask_b32_e32 v56, v134, v56, vcc
	v_cmp_le_i32_e32 vcc, v36, v147
	v_add_u32_e32 v36, 0xffffff6b, v152
	s_nop 0
	v_cndmask_b32_e32 v158, v134, v41, vcc
	v_cmp_le_i32_e32 vcc, v36, v147
	v_add_u32_e32 v36, 0xffffff50, v152
	v_exp_f32_e32 v41, v53
	v_cndmask_b32_e32 v57, v134, v57, vcc
	v_cmp_le_i32_e32 vcc, v36, v147
	v_add_u32_e32 v36, 0xffffff70, v152
	v_exp_f32_e32 v51, v57
	v_cndmask_b32_e32 v159, v134, v42, vcc
	v_cmp_le_i32_e32 vcc, v36, v147
	v_add_u32_e32 v36, 0xffffff51, v152
	v_exp_f32_e32 v52, v159
	v_cndmask_b32_e32 v58, v134, v58, vcc
	v_cmp_le_i32_e32 vcc, v36, v147
	v_add_u32_e32 v36, 0xffffff71, v152
	s_nop 0
	v_cndmask_b32_e32 v160, v134, v43, vcc
	v_cmp_le_i32_e32 vcc, v36, v147
	v_add_u32_e32 v36, 0xffffff52, v152
	v_pk_add_f32 v[42:43], v[34:35], 0 op_sel_hi:[1,0]
	v_cndmask_b32_e32 v59, v134, v59, vcc
	v_cmp_le_i32_e32 vcc, v36, v147
	v_add_u32_e32 v36, 0xffffff72, v152
	v_exp_f32_e32 v53, v160
	v_cndmask_b32_e32 v161, v134, v44, vcc
	v_cmp_le_i32_e32 vcc, v36, v147
	v_add_u32_e32 v36, 0xffffff53, v152
	v_exp_f32_e32 v44, v155
	v_cndmask_b32_e32 v60, v134, v60, vcc
	v_cmp_le_i32_e32 vcc, v36, v147
	v_add_u32_e32 v36, 0xffffff73, v152
	v_cvt_pk_bf16_f32 v155, v38, v39
	v_cndmask_b32_e32 v162, v134, v45, vcc
	v_cmp_le_i32_e32 vcc, v36, v147
	v_add_u32_e32 v36, 0xffffff58, v152
	v_exp_f32_e32 v45, v156
	v_cndmask_b32_e32 v61, v134, v61, vcc
	v_cmp_le_i32_e32 vcc, v36, v147
	v_add_u32_e32 v36, 0xffffff78, v152
	v_exp_f32_e32 v57, v162
	v_cndmask_b32_e32 v163, v134, v46, vcc
	v_cmp_le_i32_e32 vcc, v36, v147
	v_add_u32_e32 v36, 0xffffff59, v152
	v_exp_f32_e32 v46, v54
	v_cndmask_b32_e32 v62, v134, v62, vcc
	v_cmp_le_i32_e32 vcc, v36, v147
	v_add_u32_e32 v36, 0xffffff79, v152
	v_exp_f32_e32 v54, v58
	v_cndmask_b32_e32 v164, v134, v47, vcc
	v_cmp_le_i32_e32 vcc, v36, v147
	v_add_u32_e32 v36, 0xffffff5a, v152
	v_exp_f32_e32 v47, v55
	v_cndmask_b32_e32 v63, v134, v63, vcc
	v_cmp_le_i32_e32 vcc, v36, v147
	v_add_u32_e32 v36, 0xffffff7a, v152
	v_exp_f32_e32 v55, v59
	v_cndmask_b32_e32 v165, v134, v48, vcc
	v_cmp_le_i32_e32 vcc, v36, v147
	v_add_u32_e32 v36, 0xffffff5b, v152
	v_exp_f32_e32 v48, v157
	v_cndmask_b32_e32 v166, v134, v64, vcc
	v_cmp_le_i32_e32 vcc, v36, v147
	v_add_u32_e32 v36, 0xffffff7b, v152
	v_exp_f32_e32 v58, v60
	v_cndmask_b32_e32 v167, v134, v49, vcc
	v_cmp_le_i32_e32 vcc, v36, v147
	v_exp_f32_e32 v36, v50
	v_exp_f32_e32 v49, v158
	v_exp_f32_e32 v50, v56
	v_exp_f32_e32 v56, v161
	v_pk_add_f32 v[42:43], v[36:37], v[42:43]
	v_exp_f32_e32 v59, v61
	v_pk_add_f32 v[42:43], v[38:39], v[42:43]
	v_exp_f32_e32 v64, v165
	v_pk_add_f32 v[42:43], v[40:41], v[42:43]
	v_cvt_pk_bf16_f32 v165, v50, v51
	v_pk_add_f32 v[42:43], v[44:45], v[42:43]
	v_exp_f32_e32 v60, v163
	v_pk_add_f32 v[42:43], v[46:47], v[42:43]
	v_exp_f32_e32 v61, v164
	v_pk_add_f32 v[42:43], v[48:49], v[42:43]
	v_cvt_pk_bf16_f32 v158, v52, v53
	v_pk_add_f32 v[42:43], v[50:51], v[42:43]
	ds_read_b64_tr_b16 v[50:51],v0 offset:0
	v_exp_f32_e32 v62, v62
	v_pk_add_f32 v[42:43], v[52:53], v[42:43]
	ds_read_b64_tr_b16 v[52:53],v0 offset:512
	v_exp_f32_e32 v63, v63
	v_pk_add_f32 v[42:43], v[54:55], v[42:43]
	v_exp_f32_e32 v170, v166
	v_cvt_pk_bf16_f32 v166, v54, v55
	ds_read_b64_tr_b16 v[54:55],v0 offset:1024
	v_cndmask_b32_e32 v152, v134, v65, vcc
	v_pk_add_f32 v[42:43], v[56:57], v[42:43]
	v_exp_f32_e32 v65, v167
	v_cvt_pk_bf16_f32 v159, v56, v57
	ds_read_b64_tr_b16 v[56:57],v0 offset:1536
	v_pk_add_f32 v[42:43], v[58:59], v[42:43]
	v_exp_f32_e32 v171, v152
	v_cvt_pk_bf16_f32 v167, v58, v59
	ds_read_b64_tr_b16 v[58:59],v0 offset:2048
	v_pk_add_f32 v[42:43], v[60:61], v[42:43]
	v_cvt_pk_bf16_f32 v160, v60, v61
	ds_read_b64_tr_b16 v[60:61],v0 offset:2560
	v_pk_add_f32 v[42:43], v[62:63], v[42:43]
	v_cvt_pk_bf16_f32 v168, v62, v63
	ds_read_b64_tr_b16 v[62:63],v0 offset:3072
	v_pk_add_f32 v[42:43], v[64:65], v[42:43]
	v_cvt_pk_bf16_f32 v161, v64, v65
	ds_read_b64_tr_b16 v[64:65],v0 offset:3584
	v_pk_add_f32 v[42:43], v[170:171], v[42:43]
	s_waitcnt lgkmcnt(0)
	v_cvt_pk_bf16_f32 v156, v44, v45
	v_add_f32_e32 v42, v42, v43
	v_add_f32_e32 v152, v148, v42
	v_cvt_pk_bf16_f32 v157, v48, v49
	v_cvt_pk_bf16_f32 v162, v36, v37
	v_cvt_pk_bf16_f32 v163, v40, v41
	v_cvt_pk_bf16_f32 v164, v46, v47
	v_cvt_pk_bf16_f32 v169, v170, v171
	v_mfma_f32_32x32x16_bf16 v[2:17], v[154:157], v[50:53], v[2:17]
	ds_read_b64_tr_b16 v[170:171],v0 offset:4096
	ds_read_b64_tr_b16 v[172:173],v0 offset:4608
	ds_read_b64_tr_b16 v[174:175],v0 offset:5120
	ds_read_b64_tr_b16 v[176:177],v0 offset:5632
	ds_read_b64_tr_b16 v[178:179],v0 offset:6144
	ds_read_b64_tr_b16 v[180:181],v0 offset:6656
	ds_read_b64_tr_b16 v[182:183],v0 offset:7168
	v_mfma_f32_32x32x16_bf16 v[2:17], v[158:161], v[54:57], v[2:17]
	ds_read_b64_tr_b16 v[184:185],v0 offset:7680
	s_waitcnt lgkmcnt(0)
	v_mfma_f32_32x32x16_bf16 v[2:17], v[162:165], v[58:61], v[2:17]
	v_mfma_f32_32x32x16_bf16 v[2:17], v[166:169], v[62:65], v[2:17]
	v_mfma_f32_32x32x16_bf16 v[18:33], v[154:157], v[170:173], v[18:33]
	s_mov_b64 s[68:69], 0
	v_mfma_f32_32x32x16_bf16 v[18:33], v[158:161], v[174:177], v[18:33]
	v_mfma_f32_32x32x16_bf16 v[18:33], v[162:165], v[178:181], v[18:33]
	v_mfma_f32_32x32x16_bf16 v[18:33], v[166:169], v[182:185], v[18:33]

; __global__ void __launch_bounds__(NTHR, 2) hymba_fwd(Params P) {
	.amdhsa_kernel _Z9hymba_fwd6Params
		.amdhsa_group_segment_fixed_size 0
		.amdhsa_private_segment_fixed_size 0
		.amdhsa_kernarg_size 488
		.amdhsa_user_sgpr_count 2
		.amdhsa_user_sgpr_dispatch_ptr 0
		.amdhsa_user_sgpr_queue_ptr 0
		.amdhsa_user_sgpr_kernarg_segment_ptr 1
		.amdhsa_user_sgpr_dispatch_id 0
		.amdhsa_user_sgpr_kernarg_preload_length 0
		.amdhsa_user_sgpr_kernarg_preload_offset 0
		.amdhsa_user_sgpr_private_segment_size 0
		.amdhsa_uses_dynamic_stack 0
		.amdhsa_enable_private_segment 0
		.amdhsa_system_sgpr_workgroup_id_x 1
		.amdhsa_system_sgpr_workgroup_id_y 0
		.amdhsa_system_sgpr_workgroup_id_z 0
		.amdhsa_system_sgpr_workgroup_info 0
		.amdhsa_system_vgpr_workitem_id 2
		.amdhsa_next_free_vgpr 256
		.amdhsa_next_free_sgpr 102
		.amdhsa_accum_offset 256
		.amdhsa_reserve_vcc 1
		.amdhsa_float_round_mode_32 0
		.amdhsa_float_round_mode_16_64 0
		.amdhsa_float_denorm_mode_32 3
		.amdhsa_float_denorm_mode_16_64 3
		.amdhsa_dx10_clamp 1
		.amdhsa_ieee_mode 1
		.amdhsa_fp16_overflow 0
		.amdhsa_tg_split 0
		.amdhsa_exception_fp_ieee_invalid_op 0
		.amdhsa_exception_fp_denorm_src 0
		.amdhsa_exception_fp_ieee_div_zero 0
		.amdhsa_exception_fp_ieee_overflow 0
		.amdhsa_exception_fp_ieee_underflow 0
		.amdhsa_exception_fp_ieee_inexact 0
		.amdhsa_exception_int_div_zero 0
	.end_amdhsa_kernel

; __global__ void __launch_bounds__(NTHR, 2) hymba_fwd(Params P) {
amdhsa.kernels:
  - .agpr_count:     0
    .args:
      - .offset:         0
        .size:           232
        .value_kind:     by_value
      - .offset:         232
        .size:           4
        .value_kind:     hidden_block_count_x
      - .offset:         236
        .size:           4
        .value_kind:     hidden_block_count_y
      - .offset:         240
        .size:           4
        .value_kind:     hidden_block_count_z
      - .offset:         244
        .size:           2
        .value_kind:     hidden_group_size_x
      - .offset:         246
        .size:           2
        .value_kind:     hidden_group_size_y
      - .offset:         248
        .size:           2
        .value_kind:     hidden_group_size_z
      - .offset:         250
        .size:           2
        .value_kind:     hidden_remainder_x
      - .offset:         252
        .size:           2
        .value_kind:     hidden_remainder_y
      - .offset:         254
        .size:           2
        .value_kind:     hidden_remainder_z
      - .offset:         272
        .size:           8
        .value_kind:     hidden_global_offset_x
      - .offset:         280
        .size:           8
        .value_kind:     hidden_global_offset_y
      - .offset:         288
        .size:           8
        .value_kind:     hidden_global_offset_z
      - .offset:         296
        .size:           2
        .value_kind:     hidden_grid_dims
      - .offset:         320
        .size:           8
        .value_kind:     hidden_multigrid_sync_arg
      - .offset:         352
        .size:           4
        .value_kind:     hidden_dynamic_lds_size
    .group_segment_fixed_size: 0
    .kernarg_segment_align: 8
    .kernarg_segment_size: 488
    .language:       OpenCL C
    .language_version:
      - 2
      - 0
    .max_flat_workgroup_size: 512
    .name:           _Z9hymba_fwd6Params
    .private_segment_fixed_size: 0
    .sgpr_count:     108
    .sgpr_spill_count: 42
    .symbol:         _Z9hymba_fwd6Params.kd
    .uniform_work_group_size: 1
    .uses_dynamic_stack: false
    .vgpr_count:     256
    .vgpr_spill_count: 0
    .wavefront_size: 64
